# combination: adds DPP top-k butterflies, batched page-table lookups and 3-slice prefetch in compression units
# baseline (speedup 1.0000x reference)
.LBB0_1169:
	s_and_b64 vcc, exec, s[6:7]
	s_cbranch_vccz .LBB0_1108
	s_lshl_b32 s6, s26, 2
	s_add_i32 s6, s27, s6
	s_cmpk_lt_i32 s6, 0x800
	s_cselect_b64 s[8:9], -1, 0
	s_add_i32 s7, s6, 0xfffff800
	s_cmpk_gt_i32 s6, 0x7ff
	s_cselect_b32 s11, s7, s6
	s_and_b32 s46, s11, 7
	s_lshl_b32 s7, s11, 3
	s_and_b32 s47, s7, 64
	s_lshl_b32 s16, s46, 8
	v_or_b32_e32 v8, s47, v1
	s_and_b32 s10, s6, -16
	v_lshl_add_u64 v[2:3], v[120:121], 0, s[16:17]
	s_and_b64 vcc, exec, s[8:9]
	s_cbranch_vccnz .Lp4_S
	s_mov_b64 s[6:7], -1
	s_and_b64 vcc, exec, s[8:9]
	s_cbranch_vccz .LBB0_1172
	v_lshrrev_b32_e32 v4, 3, v8
	v_or_b32_e32 v4, s10, v4
	v_ashrrev_i32_e32 v5, 31, v4
	v_lshl_add_u64 v[4:5], v[4:5], 2, s[84:85]
	global_load_dword v4, v[4:5], off
	s_mov_b64 s[6:7], 0
	s_waitcnt vmcnt(0)
	v_ashrrev_i32_e32 v5, 31, v4
	v_lshlrev_b64 v[4:5], 18, v[4:5]
	v_lshl_add_u64 v[4:5], v[2:3], 0, v[4:5]
	v_lshl_add_u64 v[18:19], v[4:5], 0, v[118:119]

.Lp4_S:
	v_lshrrev_b32_e32 v10, 3, v8
	v_add_u32_e32 v9, 16, v8
	v_or_b32_e32 v10, s10, v10
	v_lshrrev_b32_e32 v12, 3, v9
	v_or_b32_e32 v9, 32, v8
	v_or_b32_e32 v12, s10, v12
	v_lshrrev_b32_e32 v14, 3, v9
	v_add_u32_e32 v9, 48, v8
	v_or_b32_e32 v14, s10, v14
	v_lshrrev_b32_e32 v16, 3, v9
	v_add_u32_e32 v16, s10, v16
	v_ashrrev_i32_e32 v11, 31, v10
	v_ashrrev_i32_e32 v13, 31, v12
	v_ashrrev_i32_e32 v15, 31, v14
	v_ashrrev_i32_e32 v17, 31, v16
	v_lshl_add_u64 v[10:11], v[10:11], 2, s[84:85]
	v_lshl_add_u64 v[12:13], v[12:13], 2, s[84:85]
	v_lshl_add_u64 v[14:15], v[14:15], 2, s[84:85]
	v_lshl_add_u64 v[16:17], v[16:17], 2, s[84:85]
	global_load_dword v10, v[10:11], off
	global_load_dword v12, v[12:13], off
	global_load_dword v14, v[14:15], off
	global_load_dword v16, v[16:17], off
	s_ashr_i32 s26, s11, 4
	s_ashr_i32 s27, s26, 31
	s_mov_b64 s[28:29], 0x18a35000
	s_waitcnt vmcnt(0)
	v_ashrrev_i32_e32 v11, 31, v10
	v_ashrrev_i32_e32 v13, 31, v12
	v_ashrrev_i32_e32 v15, 31, v14
	v_ashrrev_i32_e32 v17, 31, v16
	v_lshlrev_b64 v[10:11], 18, v[10:11]
	v_lshlrev_b64 v[12:13], 18, v[12:13]
	v_lshlrev_b64 v[14:15], 18, v[14:15]
	v_lshlrev_b64 v[16:17], 18, v[16:17]
	v_lshl_add_u64 v[10:11], v[2:3], 0, v[10:11]
	v_lshl_add_u64 v[12:13], v[2:3], 0, v[12:13]
	v_lshl_add_u64 v[14:15], v[2:3], 0, v[14:15]
	v_lshl_add_u64 v[16:17], v[2:3], 0, v[16:17]
	v_lshl_add_u64 v[18:19], v[10:11], 0, v[118:119]
	v_lshl_add_u64 v[20:21], v[12:13], 0, v[118:119]
	v_lshl_add_u64 v[24:25], v[14:15], 0, v[118:119]
	v_lshl_add_u64 v[30:31], v[16:17], 0, v[118:119]
	s_branch .LBB0_1186

.LBB0_1186:
	s_lshl_b32 s16, s46, 18
	v_lshl_add_u64 v[22:23], v[128:129], 0, s[16:17]
	s_mov_b64 s[6:7], 0x10000
	s_mov_b64 s[8:9], 0x20000
	s_mov_b64 s[10:11], 0x30000
	s_mov_b64 s[12:13], 0x1000
	v_lshl_add_u64 v[26:27], v[22:23], 0, s[6:7]
	v_lshl_add_u64 v[28:29], v[22:23], 0, s[8:9]
	v_lshl_add_u64 v[32:33], v[22:23], 0, s[10:11]
	v_lshl_add_u64 v[18:19], v[18:19], 0, s[12:13]
	v_lshl_add_u64 v[20:21], v[20:21], 0, s[12:13]
	v_lshl_add_u64 v[24:25], v[24:25], 0, s[12:13]
	v_lshl_add_u64 v[30:31], v[30:31], 0, s[12:13]
	s_mov_b64 s[12:13], 0x2000
	v_add_u32_e32 v135, s41, v174
	v_add_u32_e32 v158, s41, v173
	global_load_dwordx4 v[36:39], v[18:19], off offset:-4096 nt
	global_load_dwordx4 v[40:43], v[20:21], off offset:-4096 nt
	global_load_dwordx4 v[44:47], v[24:25], off offset:-4096 nt
	global_load_dwordx4 v[48:51], v[30:31], off offset:-4096 nt
	global_load_dwordx4 v[52:55], v[22:23], off
	global_load_dwordx4 v[56:59], v[26:27], off
	global_load_dwordx4 v[60:63], v[28:29], off
	global_load_dwordx4 v[64:67], v[32:33], off
	global_load_dwordx4 v[68:71], v[18:19], off nt
	global_load_dwordx4 v[72:75], v[20:21], off nt
	global_load_dwordx4 v[76:79], v[24:25], off nt
	global_load_dwordx4 v[80:83], v[30:31], off nt
	global_load_dwordx4 v[84:87], v[22:23], off offset:256
	global_load_dwordx4 v[88:91], v[26:27], off offset:256
	global_load_dwordx4 v[92:95], v[28:29], off offset:256
	global_load_dwordx4 v[96:99], v[32:33], off offset:256
	v_lshl_add_u64 v[18:19], v[18:19], 0, s[12:13]
	v_lshl_add_u64 v[20:21], v[20:21], 0, s[12:13]
	v_lshl_add_u64 v[24:25], v[24:25], 0, s[12:13]
	v_lshl_add_u64 v[30:31], v[30:31], 0, s[12:13]
	global_load_dwordx4 v[214:217], v[18:19], off offset:-4096 nt
	global_load_dwordx4 v[218:221], v[20:21], off offset:-4096 nt
	global_load_dwordx4 v[222:225], v[24:25], off offset:-4096 nt
	global_load_dwordx4 v[226:229], v[30:31], off offset:-4096 nt
	global_load_dwordx4 v[230:233], v[22:23], off offset:512
	global_load_dwordx4 v[234:237], v[26:27], off offset:512
	global_load_dwordx4 v[238:241], v[28:29], off offset:512
	global_load_dwordx4 v[242:245], v[32:33], off offset:512
	s_waitcnt vmcnt(16)
	v_cvt_pk_bf16_f32 v36, v36, v37
	v_cvt_pk_bf16_f32 v37, v38, v39
	v_cvt_pk_bf16_f32 v40, v40, v41
	v_cvt_pk_bf16_f32 v41, v42, v43
	v_cvt_pk_bf16_f32 v44, v44, v45
	v_cvt_pk_bf16_f32 v45, v46, v47
	v_cvt_pk_bf16_f32 v48, v48, v49
	v_cvt_pk_bf16_f32 v49, v50, v51
	ds_write_b64 v199, v[36:37]
	ds_write_b128 v174, v[52:55] offset:17408
	ds_write_b64 v199, v[40:41] offset:4352
	ds_write_b128 v174, v[56:59] offset:26112
	ds_write_b64 v199, v[44:45] offset:8704
	ds_write_b128 v174, v[60:63] offset:34816
	ds_write_b64 v199, v[48:49] offset:13056
	ds_write_b128 v174, v[64:67] offset:43520
	s_waitcnt lgkmcnt(0)
	s_barrier
	global_load_dwordx4 v[36:39], v[18:19], off nt
	global_load_dwordx4 v[40:43], v[20:21], off nt
	global_load_dwordx4 v[44:47], v[24:25], off nt
	global_load_dwordx4 v[48:51], v[30:31], off nt
	global_load_dwordx4 v[52:55], v[22:23], off offset:768
	global_load_dwordx4 v[56:59], v[26:27], off offset:768
	global_load_dwordx4 v[60:63], v[28:29], off offset:768
	global_load_dwordx4 v[64:67], v[32:33], off offset:768
	ds_read_b128 v[136:139], v200
	ds_read_b128 v[140:143], v173 offset:17408
	ds_read_b128 v[144:147], v200 offset:32
	ds_read_b128 v[148:151], v173 offset:17440
	s_waitcnt lgkmcnt(2)
	v_mfma_f32_32x32x16_bf16 v[2:17], v[136:139], v[140:143], 0
	s_waitcnt lgkmcnt(0)
	v_mfma_f32_32x32x16_bf16 v[2:17], v[144:147], v[148:151], v[2:17]
	ds_read_b128 v[136:139], v200 offset:64
	ds_read_b128 v[140:143], v173 offset:17472
	ds_read_b128 v[144:147], v200 offset:96
	ds_read_b128 v[148:151], v173 offset:17504
	s_waitcnt lgkmcnt(2)
	v_mfma_f32_32x32x16_bf16 v[2:17], v[136:139], v[140:143], v[2:17]
	s_waitcnt lgkmcnt(0)
	v_mfma_f32_32x32x16_bf16 v[2:17], v[144:147], v[148:151], v[2:17]
	ds_read_b128 v[136:139], v200 offset:128
	ds_read_b128 v[140:143], v173 offset:17536
	ds_read_b128 v[144:147], v200 offset:160
	ds_read_b128 v[148:151], v173 offset:17568
	s_waitcnt lgkmcnt(2)
	v_mfma_f32_32x32x16_bf16 v[2:17], v[136:139], v[140:143], v[2:17]
	s_waitcnt lgkmcnt(0)
	v_mfma_f32_32x32x16_bf16 v[2:17], v[144:147], v[148:151], v[2:17]
	ds_read_b128 v[136:139], v200 offset:192
	ds_read_b128 v[140:143], v173 offset:17600
	ds_read_b128 v[144:147], v200 offset:224
	ds_read_b128 v[148:151], v173 offset:17632
	s_waitcnt lgkmcnt(2)
	v_mfma_f32_32x32x16_bf16 v[2:17], v[136:139], v[140:143], v[2:17]
	s_waitcnt lgkmcnt(0)
	v_mfma_f32_32x32x16_bf16 v[2:17], v[144:147], v[148:151], v[2:17]
	s_waitcnt vmcnt(16)
	v_cvt_pk_bf16_f32 v68, v68, v69
	v_cvt_pk_bf16_f32 v69, v70, v71
	v_cvt_pk_bf16_f32 v72, v72, v73
	v_cvt_pk_bf16_f32 v73, v74, v75
	v_cvt_pk_bf16_f32 v76, v76, v77
	v_cvt_pk_bf16_f32 v77, v78, v79
	v_cvt_pk_bf16_f32 v80, v80, v81
	v_cvt_pk_bf16_f32 v81, v82, v83
	ds_write_b64 v199, v[68:69] offset:52224
	ds_write_b128 v135, v[84:87]
	ds_write_b64 v199, v[72:73] offset:56576
	ds_write_b128 v135, v[88:91] offset:8704
	ds_write_b64 v199, v[76:77] offset:60928
	ds_write_b128 v135, v[92:95] offset:17408
	ds_write_b64 v199, v[80:81] offset:65280
	ds_write_b128 v135, v[96:99] offset:26112
	s_waitcnt lgkmcnt(0)
	s_barrier
	v_lshl_add_u64 v[18:19], v[18:19], 0, s[12:13]
	v_lshl_add_u64 v[20:21], v[20:21], 0, s[12:13]
	v_lshl_add_u64 v[24:25], v[24:25], 0, s[12:13]
	v_lshl_add_u64 v[30:31], v[30:31], 0, s[12:13]
	global_load_dwordx4 v[68:71], v[18:19], off offset:-4096 nt
	global_load_dwordx4 v[72:75], v[20:21], off offset:-4096 nt
	global_load_dwordx4 v[76:79], v[24:25], off offset:-4096 nt
	global_load_dwordx4 v[80:83], v[30:31], off offset:-4096 nt
	global_load_dwordx4 v[84:87], v[22:23], off offset:1024
	global_load_dwordx4 v[88:91], v[26:27], off offset:1024
	global_load_dwordx4 v[92:95], v[28:29], off offset:1024
	global_load_dwordx4 v[96:99], v[32:33], off offset:1024
	ds_read_b128 v[136:139], v200 offset:52224
	ds_read_b128 v[140:143], v158
	ds_read_b128 v[144:147], v200 offset:52256
	ds_read_b128 v[148:151], v158 offset:32
	s_waitcnt lgkmcnt(2)
	v_mfma_f32_32x32x16_bf16 v[2:17], v[136:139], v[140:143], v[2:17]
	s_waitcnt lgkmcnt(0)
	v_mfma_f32_32x32x16_bf16 v[2:17], v[144:147], v[148:151], v[2:17]
	ds_read_b128 v[136:139], v200 offset:52288
	ds_read_b128 v[140:143], v158 offset:64
	ds_read_b128 v[144:147], v200 offset:52320
	ds_read_b128 v[148:151], v158 offset:96
	s_waitcnt lgkmcnt(2)
	v_mfma_f32_32x32x16_bf16 v[2:17], v[136:139], v[140:143], v[2:17]
	s_waitcnt lgkmcnt(0)
	v_mfma_f32_32x32x16_bf16 v[2:17], v[144:147], v[148:151], v[2:17]
	ds_read_b128 v[136:139], v200 offset:52352
	ds_read_b128 v[140:143], v158 offset:128
	ds_read_b128 v[144:147], v200 offset:52384
	ds_read_b128 v[148:151], v158 offset:160
	s_waitcnt lgkmcnt(2)
	v_mfma_f32_32x32x16_bf16 v[2:17], v[136:139], v[140:143], v[2:17]
	s_waitcnt lgkmcnt(0)
	v_mfma_f32_32x32x16_bf16 v[2:17], v[144:147], v[148:151], v[2:17]
	ds_read_b128 v[136:139], v200 offset:52416
	ds_read_b128 v[140:143], v158 offset:192
	ds_read_b128 v[144:147], v200 offset:52448
	ds_read_b128 v[148:151], v158 offset:224
	s_waitcnt lgkmcnt(2)
	v_mfma_f32_32x32x16_bf16 v[2:17], v[136:139], v[140:143], v[2:17]
	s_waitcnt lgkmcnt(0)
	v_mfma_f32_32x32x16_bf16 v[2:17], v[144:147], v[148:151], v[2:17]
	s_waitcnt vmcnt(16)
	v_cvt_pk_bf16_f32 v214, v214, v215
	v_cvt_pk_bf16_f32 v215, v216, v217
	v_cvt_pk_bf16_f32 v218, v218, v219
	v_cvt_pk_bf16_f32 v219, v220, v221
	v_cvt_pk_bf16_f32 v222, v222, v223
	v_cvt_pk_bf16_f32 v223, v224, v225
	v_cvt_pk_bf16_f32 v226, v226, v227
	v_cvt_pk_bf16_f32 v227, v228, v229
	ds_write_b64 v199, v[214:215]
	ds_write_b128 v174, v[230:233] offset:17408
	ds_write_b64 v199, v[218:219] offset:4352
	ds_write_b128 v174, v[234:237] offset:26112
	ds_write_b64 v199, v[222:223] offset:8704
	ds_write_b128 v174, v[238:241] offset:34816
	ds_write_b64 v199, v[226:227] offset:13056
	ds_write_b128 v174, v[242:245] offset:43520
	s_waitcnt lgkmcnt(0)
	s_barrier
	global_load_dwordx4 v[214:217], v[18:19], off nt
	global_load_dwordx4 v[218:221], v[20:21], off nt
	global_load_dwordx4 v[222:225], v[24:25], off nt
	global_load_dwordx4 v[226:229], v[30:31], off nt
	global_load_dwordx4 v[230:233], v[22:23], off offset:1280
	global_load_dwordx4 v[234:237], v[26:27], off offset:1280
	global_load_dwordx4 v[238:241], v[28:29], off offset:1280
	global_load_dwordx4 v[242:245], v[32:33], off offset:1280
	ds_read_b128 v[136:139], v200
	ds_read_b128 v[140:143], v173 offset:17408
	ds_read_b128 v[144:147], v200 offset:32
	ds_read_b128 v[148:151], v173 offset:17440
	s_waitcnt lgkmcnt(2)
	v_mfma_f32_32x32x16_bf16 v[2:17], v[136:139], v[140:143], v[2:17]
	s_waitcnt lgkmcnt(0)
	v_mfma_f32_32x32x16_bf16 v[2:17], v[144:147], v[148:151], v[2:17]
	ds_read_b128 v[136:139], v200 offset:64
	ds_read_b128 v[140:143], v173 offset:17472
	ds_read_b128 v[144:147], v200 offset:96
	ds_read_b128 v[148:151], v173 offset:17504
	s_waitcnt lgkmcnt(2)
	v_mfma_f32_32x32x16_bf16 v[2:17], v[136:139], v[140:143], v[2:17]
	s_waitcnt lgkmcnt(0)
	v_mfma_f32_32x32x16_bf16 v[2:17], v[144:147], v[148:151], v[2:17]
	ds_read_b128 v[136:139], v200 offset:128
	ds_read_b128 v[140:143], v173 offset:17536
	ds_read_b128 v[144:147], v200 offset:160
	ds_read_b128 v[148:151], v173 offset:17568
	s_waitcnt lgkmcnt(2)
	v_mfma_f32_32x32x16_bf16 v[2:17], v[136:139], v[140:143], v[2:17]
	s_waitcnt lgkmcnt(0)
	v_mfma_f32_32x32x16_bf16 v[2:17], v[144:147], v[148:151], v[2:17]
	ds_read_b128 v[136:139], v200 offset:192
	ds_read_b128 v[140:143], v173 offset:17600
	ds_read_b128 v[144:147], v200 offset:224
	ds_read_b128 v[148:151], v173 offset:17632
	s_waitcnt lgkmcnt(2)
	v_mfma_f32_32x32x16_bf16 v[2:17], v[136:139], v[140:143], v[2:17]
	s_waitcnt lgkmcnt(0)
	v_mfma_f32_32x32x16_bf16 v[2:17], v[144:147], v[148:151], v[2:17]
	s_waitcnt vmcnt(16)
	v_cvt_pk_bf16_f32 v36, v36, v37
	v_cvt_pk_bf16_f32 v37, v38, v39
	v_cvt_pk_bf16_f32 v40, v40, v41
	v_cvt_pk_bf16_f32 v41, v42, v43
	v_cvt_pk_bf16_f32 v44, v44, v45
	v_cvt_pk_bf16_f32 v45, v46, v47
	v_cvt_pk_bf16_f32 v48, v48, v49
	v_cvt_pk_bf16_f32 v49, v50, v51
	ds_write_b64 v199, v[36:37] offset:52224
	ds_write_b128 v135, v[52:55]
	ds_write_b64 v199, v[40:41] offset:56576
	ds_write_b128 v135, v[56:59] offset:8704
	ds_write_b64 v199, v[44:45] offset:60928
	ds_write_b128 v135, v[60:63] offset:17408
	ds_write_b64 v199, v[48:49] offset:65280
	ds_write_b128 v135, v[64:67] offset:26112
	s_waitcnt lgkmcnt(0)
	s_barrier
	v_lshl_add_u64 v[18:19], v[18:19], 0, s[12:13]
	v_lshl_add_u64 v[20:21], v[20:21], 0, s[12:13]
	v_lshl_add_u64 v[24:25], v[24:25], 0, s[12:13]
	v_lshl_add_u64 v[30:31], v[30:31], 0, s[12:13]
	global_load_dwordx4 v[36:39], v[18:19], off offset:-4096 nt
	global_load_dwordx4 v[40:43], v[20:21], off offset:-4096 nt
	global_load_dwordx4 v[44:47], v[24:25], off offset:-4096 nt
	global_load_dwordx4 v[48:51], v[30:31], off offset:-4096 nt
	global_load_dwordx4 v[52:55], v[22:23], off offset:1536
	global_load_dwordx4 v[56:59], v[26:27], off offset:1536
	global_load_dwordx4 v[60:63], v[28:29], off offset:1536
	global_load_dwordx4 v[64:67], v[32:33], off offset:1536
	ds_read_b128 v[136:139], v200 offset:52224
	ds_read_b128 v[140:143], v158
	ds_read_b128 v[144:147], v200 offset:52256
	ds_read_b128 v[148:151], v158 offset:32
	s_waitcnt lgkmcnt(2)
	v_mfma_f32_32x32x16_bf16 v[2:17], v[136:139], v[140:143], v[2:17]
	s_waitcnt lgkmcnt(0)
	v_mfma_f32_32x32x16_bf16 v[2:17], v[144:147], v[148:151], v[2:17]
	ds_read_b128 v[136:139], v200 offset:52288
	ds_read_b128 v[140:143], v158 offset:64
	ds_read_b128 v[144:147], v200 offset:52320
	ds_read_b128 v[148:151], v158 offset:96
	s_waitcnt lgkmcnt(2)
	v_mfma_f32_32x32x16_bf16 v[2:17], v[136:139], v[140:143], v[2:17]
	s_waitcnt lgkmcnt(0)
	v_mfma_f32_32x32x16_bf16 v[2:17], v[144:147], v[148:151], v[2:17]
	ds_read_b128 v[136:139], v200 offset:52352
	ds_read_b128 v[140:143], v158 offset:128
	ds_read_b128 v[144:147], v200 offset:52384
	ds_read_b128 v[148:151], v158 offset:160
	s_waitcnt lgkmcnt(2)
	v_mfma_f32_32x32x16_bf16 v[2:17], v[136:139], v[140:143], v[2:17]
	s_waitcnt lgkmcnt(0)
	v_mfma_f32_32x32x16_bf16 v[2:17], v[144:147], v[148:151], v[2:17]
	ds_read_b128 v[136:139], v200 offset:52416
	ds_read_b128 v[140:143], v158 offset:192
	ds_read_b128 v[144:147], v200 offset:52448
	ds_read_b128 v[148:151], v158 offset:224
	s_waitcnt lgkmcnt(2)
	v_mfma_f32_32x32x16_bf16 v[2:17], v[136:139], v[140:143], v[2:17]
	s_waitcnt lgkmcnt(0)
	v_mfma_f32_32x32x16_bf16 v[2:17], v[144:147], v[148:151], v[2:17]
	s_waitcnt vmcnt(16)
	v_cvt_pk_bf16_f32 v68, v68, v69
	v_cvt_pk_bf16_f32 v69, v70, v71
	v_cvt_pk_bf16_f32 v72, v72, v73
	v_cvt_pk_bf16_f32 v73, v74, v75
	v_cvt_pk_bf16_f32 v76, v76, v77
	v_cvt_pk_bf16_f32 v77, v78, v79
	v_cvt_pk_bf16_f32 v80, v80, v81
	v_cvt_pk_bf16_f32 v81, v82, v83
	ds_write_b64 v199, v[68:69]
	ds_write_b128 v174, v[84:87] offset:17408
	ds_write_b64 v199, v[72:73] offset:4352
	ds_write_b128 v174, v[88:91] offset:26112
	ds_write_b64 v199, v[76:77] offset:8704
	ds_write_b128 v174, v[92:95] offset:34816
	ds_write_b64 v199, v[80:81] offset:13056
	ds_write_b128 v174, v[96:99] offset:43520
	s_waitcnt lgkmcnt(0)
	s_barrier
	global_load_dwordx4 v[68:71], v[18:19], off nt
	global_load_dwordx4 v[72:75], v[20:21], off nt
	global_load_dwordx4 v[76:79], v[24:25], off nt
	global_load_dwordx4 v[80:83], v[30:31], off nt
	global_load_dwordx4 v[84:87], v[22:23], off offset:1792
	global_load_dwordx4 v[88:91], v[26:27], off offset:1792
	global_load_dwordx4 v[92:95], v[28:29], off offset:1792
	global_load_dwordx4 v[96:99], v[32:33], off offset:1792
	ds_read_b128 v[136:139], v200
	ds_read_b128 v[140:143], v173 offset:17408
	ds_read_b128 v[144:147], v200 offset:32
	ds_read_b128 v[148:151], v173 offset:17440
	s_waitcnt lgkmcnt(2)
	v_mfma_f32_32x32x16_bf16 v[2:17], v[136:139], v[140:143], v[2:17]
	s_waitcnt lgkmcnt(0)
	v_mfma_f32_32x32x16_bf16 v[2:17], v[144:147], v[148:151], v[2:17]
	ds_read_b128 v[136:139], v200 offset:64
	ds_read_b128 v[140:143], v173 offset:17472
	ds_read_b128 v[144:147], v200 offset:96
	ds_read_b128 v[148:151], v173 offset:17504
	s_waitcnt lgkmcnt(2)
	v_mfma_f32_32x32x16_bf16 v[2:17], v[136:139], v[140:143], v[2:17]
	s_waitcnt lgkmcnt(0)
	v_mfma_f32_32x32x16_bf16 v[2:17], v[144:147], v[148:151], v[2:17]
	ds_read_b128 v[136:139], v200 offset:128
	ds_read_b128 v[140:143], v173 offset:17536
	ds_read_b128 v[144:147], v200 offset:160
	ds_read_b128 v[148:151], v173 offset:17568
	s_waitcnt lgkmcnt(2)
	v_mfma_f32_32x32x16_bf16 v[2:17], v[136:139], v[140:143], v[2:17]
	s_waitcnt lgkmcnt(0)
	v_mfma_f32_32x32x16_bf16 v[2:17], v[144:147], v[148:151], v[2:17]
	ds_read_b128 v[136:139], v200 offset:192
	ds_read_b128 v[140:143], v173 offset:17600
	ds_read_b128 v[144:147], v200 offset:224
	ds_read_b128 v[148:151], v173 offset:17632
	s_waitcnt lgkmcnt(2)
	v_mfma_f32_32x32x16_bf16 v[2:17], v[136:139], v[140:143], v[2:17]
	s_waitcnt lgkmcnt(0)
	v_mfma_f32_32x32x16_bf16 v[2:17], v[144:147], v[148:151], v[2:17]
	s_waitcnt vmcnt(16)
	v_cvt_pk_bf16_f32 v214, v214, v215
	v_cvt_pk_bf16_f32 v215, v216, v217
	v_cvt_pk_bf16_f32 v218, v218, v219
	v_cvt_pk_bf16_f32 v219, v220, v221
	v_cvt_pk_bf16_f32 v222, v222, v223
	v_cvt_pk_bf16_f32 v223, v224, v225
	v_cvt_pk_bf16_f32 v226, v226, v227
	v_cvt_pk_bf16_f32 v227, v228, v229
	ds_write_b64 v199, v[214:215] offset:52224
	ds_write_b128 v135, v[230:233]
	ds_write_b64 v199, v[218:219] offset:56576
	ds_write_b128 v135, v[234:237] offset:8704
	ds_write_b64 v199, v[222:223] offset:60928
	ds_write_b128 v135, v[238:241] offset:17408
	ds_write_b64 v199, v[226:227] offset:65280
	ds_write_b128 v135, v[242:245] offset:26112
	s_waitcnt lgkmcnt(0)
	s_barrier
	ds_read_b128 v[136:139], v200 offset:52224
	ds_read_b128 v[140:143], v158
	ds_read_b128 v[144:147], v200 offset:52256
	ds_read_b128 v[148:151], v158 offset:32
	s_waitcnt lgkmcnt(2)
	v_mfma_f32_32x32x16_bf16 v[2:17], v[136:139], v[140:143], v[2:17]
	s_waitcnt lgkmcnt(0)
	v_mfma_f32_32x32x16_bf16 v[2:17], v[144:147], v[148:151], v[2:17]
	ds_read_b128 v[136:139], v200 offset:52288
	ds_read_b128 v[140:143], v158 offset:64
	ds_read_b128 v[144:147], v200 offset:52320
	ds_read_b128 v[148:151], v158 offset:96
	s_waitcnt lgkmcnt(2)
	v_mfma_f32_32x32x16_bf16 v[2:17], v[136:139], v[140:143], v[2:17]
	s_waitcnt lgkmcnt(0)
	v_mfma_f32_32x32x16_bf16 v[2:17], v[144:147], v[148:151], v[2:17]
	ds_read_b128 v[136:139], v200 offset:52352
	ds_read_b128 v[140:143], v158 offset:128
	ds_read_b128 v[144:147], v200 offset:52384
	ds_read_b128 v[148:151], v158 offset:160
	s_waitcnt lgkmcnt(2)
	v_mfma_f32_32x32x16_bf16 v[2:17], v[136:139], v[140:143], v[2:17]
	s_waitcnt lgkmcnt(0)
	v_mfma_f32_32x32x16_bf16 v[2:17], v[144:147], v[148:151], v[2:17]
	ds_read_b128 v[136:139], v200 offset:52416
	ds_read_b128 v[140:143], v158 offset:192
	ds_read_b128 v[144:147], v200 offset:52448
	ds_read_b128 v[148:151], v158 offset:224
	s_waitcnt lgkmcnt(2)
	v_mfma_f32_32x32x16_bf16 v[2:17], v[136:139], v[140:143], v[2:17]
	s_waitcnt lgkmcnt(0)
	v_mfma_f32_32x32x16_bf16 v[2:17], v[144:147], v[148:151], v[2:17]
	s_waitcnt vmcnt(8)
	v_cvt_pk_bf16_f32 v36, v36, v37
	v_cvt_pk_bf16_f32 v37, v38, v39
	v_cvt_pk_bf16_f32 v40, v40, v41
	v_cvt_pk_bf16_f32 v41, v42, v43
	v_cvt_pk_bf16_f32 v44, v44, v45
	v_cvt_pk_bf16_f32 v45, v46, v47
	v_cvt_pk_bf16_f32 v48, v48, v49
	v_cvt_pk_bf16_f32 v49, v50, v51
	ds_write_b64 v199, v[36:37]
	ds_write_b128 v174, v[52:55] offset:17408
	ds_write_b64 v199, v[40:41] offset:4352
	ds_write_b128 v174, v[56:59] offset:26112
	ds_write_b64 v199, v[44:45] offset:8704
	ds_write_b128 v174, v[60:63] offset:34816
	ds_write_b64 v199, v[48:49] offset:13056
	ds_write_b128 v174, v[64:67] offset:43520
	s_waitcnt lgkmcnt(0)
	s_barrier
	ds_read_b128 v[136:139], v200
	ds_read_b128 v[140:143], v173 offset:17408
	ds_read_b128 v[144:147], v200 offset:32
	ds_read_b128 v[148:151], v173 offset:17440
	s_waitcnt lgkmcnt(2)
	v_mfma_f32_32x32x16_bf16 v[2:17], v[136:139], v[140:143], v[2:17]
	s_waitcnt lgkmcnt(0)
	v_mfma_f32_32x32x16_bf16 v[2:17], v[144:147], v[148:151], v[2:17]
	ds_read_b128 v[136:139], v200 offset:64
	ds_read_b128 v[140:143], v173 offset:17472
	ds_read_b128 v[144:147], v200 offset:96
	ds_read_b128 v[148:151], v173 offset:17504
	s_waitcnt lgkmcnt(2)
	v_mfma_f32_32x32x16_bf16 v[2:17], v[136:139], v[140:143], v[2:17]
	s_waitcnt lgkmcnt(0)
	v_mfma_f32_32x32x16_bf16 v[2:17], v[144:147], v[148:151], v[2:17]
	ds_read_b128 v[136:139], v200 offset:128
	ds_read_b128 v[140:143], v173 offset:17536
	ds_read_b128 v[144:147], v200 offset:160
	ds_read_b128 v[148:151], v173 offset:17568
	s_waitcnt lgkmcnt(2)
	v_mfma_f32_32x32x16_bf16 v[2:17], v[136:139], v[140:143], v[2:17]
	s_waitcnt lgkmcnt(0)
	v_mfma_f32_32x32x16_bf16 v[2:17], v[144:147], v[148:151], v[2:17]
	ds_read_b128 v[136:139], v200 offset:192
	ds_read_b128 v[140:143], v173 offset:17600
	ds_read_b128 v[144:147], v200 offset:224
	ds_read_b128 v[148:151], v173 offset:17632
	s_waitcnt lgkmcnt(2)
	v_mfma_f32_32x32x16_bf16 v[2:17], v[136:139], v[140:143], v[2:17]
	s_waitcnt lgkmcnt(0)
	v_mfma_f32_32x32x16_bf16 v[2:17], v[144:147], v[148:151], v[2:17]
	s_waitcnt vmcnt(0)
	v_cvt_pk_bf16_f32 v68, v68, v69
	v_cvt_pk_bf16_f32 v69, v70, v71
	v_cvt_pk_bf16_f32 v72, v72, v73
	v_cvt_pk_bf16_f32 v73, v74, v75
	v_cvt_pk_bf16_f32 v76, v76, v77
	v_cvt_pk_bf16_f32 v77, v78, v79
	v_cvt_pk_bf16_f32 v80, v80, v81
	v_cvt_pk_bf16_f32 v81, v82, v83
	ds_write_b64 v199, v[68:69] offset:52224
	ds_write_b128 v135, v[84:87]
	ds_write_b64 v199, v[72:73] offset:56576
	ds_write_b128 v135, v[88:91] offset:8704
	ds_write_b64 v199, v[76:77] offset:60928
	ds_write_b128 v135, v[92:95] offset:17408
	ds_write_b64 v199, v[80:81] offset:65280
	ds_write_b128 v135, v[96:99] offset:26112
	s_waitcnt lgkmcnt(0)
	s_barrier
	ds_read_b128 v[136:139], v200 offset:52224
	ds_read_b128 v[140:143], v158
	ds_read_b128 v[144:147], v200 offset:52256
	ds_read_b128 v[148:151], v158 offset:32
	s_waitcnt lgkmcnt(2)
	v_mfma_f32_32x32x16_bf16 v[2:17], v[136:139], v[140:143], v[2:17]
	s_waitcnt lgkmcnt(0)
	v_mfma_f32_32x32x16_bf16 v[2:17], v[144:147], v[148:151], v[2:17]
	ds_read_b128 v[136:139], v200 offset:52288
	ds_read_b128 v[140:143], v158 offset:64
	ds_read_b128 v[144:147], v200 offset:52320
	ds_read_b128 v[148:151], v158 offset:96
	s_waitcnt lgkmcnt(2)
	v_mfma_f32_32x32x16_bf16 v[2:17], v[136:139], v[140:143], v[2:17]
	s_waitcnt lgkmcnt(0)
	v_mfma_f32_32x32x16_bf16 v[2:17], v[144:147], v[148:151], v[2:17]
	ds_read_b128 v[136:139], v200 offset:52352
	ds_read_b128 v[140:143], v158 offset:128
	ds_read_b128 v[144:147], v200 offset:52384
	ds_read_b128 v[148:151], v158 offset:160
	s_waitcnt lgkmcnt(2)
	v_mfma_f32_32x32x16_bf16 v[2:17], v[136:139], v[140:143], v[2:17]
	s_waitcnt lgkmcnt(0)
	v_mfma_f32_32x32x16_bf16 v[2:17], v[144:147], v[148:151], v[2:17]
	ds_read_b128 v[136:139], v200 offset:52416
	ds_read_b128 v[140:143], v158 offset:192
	ds_read_b128 v[144:147], v200 offset:52448
	ds_read_b128 v[148:151], v158 offset:224
	s_waitcnt lgkmcnt(2)
	v_mfma_f32_32x32x16_bf16 v[2:17], v[136:139], v[140:143], v[2:17]
	s_waitcnt lgkmcnt(0)
	v_mfma_f32_32x32x16_bf16 v[2:17], v[144:147], v[148:151], v[2:17]
	v_and_b32_e32 v19, 64, v201
	v_xor_b32_e32 v18, 1, v201
	v_add_u32_e32 v19, 64, v19
	v_cmp_lt_i32_e32 vcc, v18, v19
	s_lshl_b64 s[6:7], s[26:27], 10
	v_add_u32_e32 v21, s47, v175
	v_cndmask_b32_e32 v18, v201, v18, vcc
	v_lshlrev_b32_e32 v20, 2, v18
	s_nop 3
	ds_bpermute_b32 v22, v20, v2
	s_or_b32 s6, s6, s46
	v_lshl_add_u64 v[18:19], v[122:123], 0, s[28:29]
	s_and_saveexec_b64 s[8:9], s[4:5]
	s_cbranch_execz .LBB0_1188
	v_lshlrev_b32_e32 v102, 3, v21
	s_waitcnt lgkmcnt(0)
	v_cvt_pk_bf16_f32 v2, v2, v22
	v_lshl_add_u64 v[22:23], s[6:7], 0, v[102:103]
	v_lshlrev_b64 v[22:23], 8, v[22:23]
	v_lshl_add_u64 v[22:23], v[18:19], 0, v[22:23]
	global_store_dword v[22:23], v2, off

.LBB0_2045:
	s_or_b64 exec, exec, s[44:45]
	s_waitcnt vmcnt(1)
	v_mov_b32_e32 v15, v8
	v_pk_add_f32 v[10:11], v[14:15], v[12:13]
	v_mov_b32_e32 v7, v13
	v_and_b32_e32 v13, 0x7fffffff, v11
	v_and_b32_e32 v12, 0x7fffffff, v10
	v_xor_b32_e32 v14, -1, v11
	v_pk_add_f32 v[12:13], v[12:13], 0 neg_lo:[1,1] neg_hi:[1,1]
	v_cmp_gt_i32_e32 vcc, 0, v11
	v_xor_b32_e32 v15, -1, v10
	v_pk_add_f32 v[6:7], v[8:9], v[6:7]
	v_cndmask_b32_e32 v11, v13, v14, vcc
	v_cmp_gt_i32_e32 vcc, 0, v10
	v_not_b32_e32 v8, v6
	v_or_b32_e32 v9, 0x80000000, v6
	v_cndmask_b32_e32 v10, v12, v15, vcc
	v_cmp_gt_i32_e32 vcc, 0, v6
	s_waitcnt vmcnt(0)
	v_pk_add_f32 v[2:3], v[2:3], v[4:5]
	v_and_b32_e32 v11, 0xffffff00, v11
	v_cndmask_b32_e32 v6, v9, v8, vcc
	v_not_b32_e32 v8, v7
	v_or_b32_e32 v9, 0x80000000, v7
	v_cmp_gt_i32_e32 vcc, 0, v7
	v_and_b32_e32 v5, 0x7fffffff, v3
	v_and_b32_e32 v4, 0x7fffffff, v2
	v_cndmask_b32_e32 v7, v9, v8, vcc
	v_xor_b32_e32 v8, -1, v3
	v_pk_add_f32 v[4:5], v[4:5], 0 neg_lo:[1,1] neg_hi:[1,1]
	v_cmp_gt_i32_e32 vcc, 0, v3
	v_xor_b32_e32 v9, -1, v2
	v_or_b32_e32 v12, v11, v105
	v_cndmask_b32_e32 v3, v5, v8, vcc
	v_cmp_gt_i32_e32 vcc, 0, v2
	v_and_b32_e32 v6, 0xffffff00, v6
	v_xor_b32_e32 v11, 0xff, v12
	v_cndmask_b32_e32 v2, v4, v9, vcc
	v_and_b32_e32 v4, 64, v168
	v_add_u32_e32 v16, 64, v4
	v_xor_b32_e32 v4, 1, v168
	v_cmp_lt_i32_e32 vcc, v4, v16
	v_bitop3_b32 v6, v6, s51, v124 bitop3:0x36
	v_and_b32_e32 v7, 0xffffff00, v7
	v_cndmask_b32_e32 v4, v168, v4, vcc
	s_movk_i32 s44, 0xff00
	v_sub_u32_e32 v7, v7, v124
	v_lshlrev_b32_e32 v67, 2, v4
	v_max_u32_e32 v4, v11, v6
	v_cmp_eq_u32_e32 vcc, s44, v12
	v_and_b32_e32 v10, 0xffffff00, v10
	v_add_u32_e32 v7, 0xef, v7
	v_cndmask_b32_e32 v4, v4, v6, vcc
	v_or_b32_e32 v10, v10, v110
	v_max_u32_e32 v4, v4, v7
	v_and_b32_e32 v3, 0xffffff00, v3
	v_max_u32_e32 v5, v4, v10
	v_cmp_eq_u32_e32 vcc, -1, v10
	v_or_b32_e32 v3, v3, v111
	v_and_b32_e32 v2, 0xffffff00, v2
	v_cndmask_b32_e32 v4, v5, v4, vcc
	v_max_u32_e32 v5, v4, v3
	v_cmp_eq_u32_e32 vcc, -1, v3
	v_or_b32_e32 v2, v2, v122
	s_lshl_b32 s44, s46, 10
	v_cndmask_b32_e32 v4, v5, v4, vcc
	v_max_u32_e32 v5, v4, v2
	v_cmp_eq_u32_e32 vcc, -1, v2
	s_mov_b32 s47, 7
	s_mov_b32 s64, -16
	v_cndmask_b32_e32 v4, v5, v4, vcc
	v_max_u32_e32 v4, v4, v18
	s_nop 1
	v_mov_b32_dpp v5, v4 quad_perm:[1,0,3,2] row_mask:0xf bank_mask:0xf
	v_mov_b32_e32 v73, v161
	v_mov_b32_e32 v74, v66
	s_waitcnt lgkmcnt(0)
	v_max_u32_e32 v4, v4, v5
	v_xor_b32_e32 v5, 2, v168
	v_cmp_lt_i32_e32 vcc, v5, v16
	s_nop 1
	v_cndmask_b32_e32 v5, v168, v5, vcc
	v_lshlrev_b32_e32 v68, 2, v5
	s_nop 1
	v_mov_b32_dpp v5, v4 quad_perm:[2,3,0,1] row_mask:0xf bank_mask:0xf
	s_waitcnt lgkmcnt(0)
	v_max_u32_e32 v4, v4, v5
	v_xor_b32_e32 v5, 4, v168
	v_cmp_lt_i32_e32 vcc, v5, v16
	s_nop 1
	v_cndmask_b32_e32 v5, v168, v5, vcc
	v_lshlrev_b32_e32 v69, 2, v5
	s_nop 1
	v_mov_b32_dpp v5, v4 row_half_mirror row_mask:0xf bank_mask:0xf
	s_waitcnt lgkmcnt(0)
	v_max_u32_e32 v4, v4, v5
	v_cmp_lt_u32_e32 vcc, v11, v4
	s_nop 1
	v_cndmask_b32_e32 v5, 0, v11, vcc
	v_max_u32_e32 v8, v5, v6
	v_cmp_lt_u32_e32 vcc, v6, v4
	s_nop 1
	v_cndmask_b32_e32 v5, v5, v8, vcc
	v_max_u32_e32 v8, v5, v7
	v_cmp_lt_u32_e32 vcc, v7, v4
	s_nop 1
	v_cndmask_b32_e32 v5, v5, v8, vcc
	v_max_u32_e32 v8, v5, v10
	v_cmp_lt_u32_e32 vcc, v10, v4
	s_nop 1
	v_cndmask_b32_e32 v5, v5, v8, vcc
	v_max_u32_e32 v8, v5, v3
	v_cmp_lt_u32_e32 vcc, v3, v4
	s_nop 1
	v_cndmask_b32_e32 v5, v5, v8, vcc
	v_max_u32_e32 v8, v5, v2
	v_cmp_lt_u32_e32 vcc, v2, v4
	s_nop 1
	v_cndmask_b32_e32 v5, v5, v8, vcc
	v_max_u32_e32 v8, v5, v18
	v_cmp_lt_u32_e32 vcc, v18, v4
	s_nop 1
	v_cndmask_b32_e32 v5, v5, v8, vcc
	s_nop 1
	v_mov_b32_dpp v8, v5 quad_perm:[1,0,3,2] row_mask:0xf bank_mask:0xf
	s_waitcnt lgkmcnt(0)
	v_max_u32_e32 v5, v5, v8
	s_nop 1
	v_mov_b32_dpp v8, v5 quad_perm:[2,3,0,1] row_mask:0xf bank_mask:0xf
	s_waitcnt lgkmcnt(0)
	v_max_u32_e32 v5, v5, v8
	s_nop 1
	v_mov_b32_dpp v8, v5 row_half_mirror row_mask:0xf bank_mask:0xf
	s_waitcnt lgkmcnt(0)
	v_max_u32_e32 v5, v5, v8
	v_cmp_lt_u32_e32 vcc, v11, v5
	s_nop 1
	v_cndmask_b32_e32 v8, 0, v11, vcc
	v_max_u32_e32 v9, v8, v6
	v_cmp_lt_u32_e32 vcc, v6, v5
	s_nop 1
	v_cndmask_b32_e32 v8, v8, v9, vcc
	v_max_u32_e32 v9, v8, v7
	v_cmp_lt_u32_e32 vcc, v7, v5
	s_nop 1
	v_cndmask_b32_e32 v8, v8, v9, vcc
	v_max_u32_e32 v9, v8, v10
	v_cmp_lt_u32_e32 vcc, v10, v5
	s_nop 1
	v_cndmask_b32_e32 v8, v8, v9, vcc
	v_max_u32_e32 v9, v8, v3
	v_cmp_lt_u32_e32 vcc, v3, v5
	s_nop 1
	v_cndmask_b32_e32 v8, v8, v9, vcc
	v_max_u32_e32 v9, v8, v2
	v_cmp_lt_u32_e32 vcc, v2, v5
	s_nop 1
	v_cndmask_b32_e32 v8, v8, v9, vcc
	v_max_u32_e32 v9, v8, v18
	v_cmp_lt_u32_e32 vcc, v18, v5
	s_nop 1
	v_cndmask_b32_e32 v8, v8, v9, vcc
	s_nop 1
	v_mov_b32_dpp v9, v8 quad_perm:[1,0,3,2] row_mask:0xf bank_mask:0xf
	s_waitcnt lgkmcnt(0)
	v_max_u32_e32 v8, v8, v9
	s_nop 1
	v_mov_b32_dpp v9, v8 quad_perm:[2,3,0,1] row_mask:0xf bank_mask:0xf
	s_waitcnt lgkmcnt(0)
	v_max_u32_e32 v8, v8, v9
	s_nop 1
	v_mov_b32_dpp v9, v8 row_half_mirror row_mask:0xf bank_mask:0xf
	s_waitcnt lgkmcnt(0)
	v_max_u32_e32 v8, v8, v9
	v_cmp_lt_u32_e32 vcc, v11, v8
	s_nop 1
	v_cndmask_b32_e32 v9, 0, v11, vcc
	v_max_u32_e32 v12, v9, v6
	v_cmp_lt_u32_e32 vcc, v6, v8
	s_nop 1
	v_cndmask_b32_e32 v9, v9, v12, vcc
	v_max_u32_e32 v12, v9, v7
	v_cmp_lt_u32_e32 vcc, v7, v8
	s_nop 1
	v_cndmask_b32_e32 v9, v9, v12, vcc
	v_max_u32_e32 v12, v9, v10
	v_cmp_lt_u32_e32 vcc, v10, v8
	s_nop 1
	v_cndmask_b32_e32 v9, v9, v12, vcc
	v_max_u32_e32 v12, v9, v3
	v_cmp_lt_u32_e32 vcc, v3, v8
	s_nop 1
	v_cndmask_b32_e32 v9, v9, v12, vcc
	v_max_u32_e32 v12, v9, v2
	v_cmp_lt_u32_e32 vcc, v2, v8
	s_nop 1
	v_cndmask_b32_e32 v9, v9, v12, vcc
	v_max_u32_e32 v12, v9, v18
	v_cmp_lt_u32_e32 vcc, v18, v8
	s_nop 1
	v_cndmask_b32_e32 v9, v9, v12, vcc
	s_nop 1
	v_mov_b32_dpp v12, v9 quad_perm:[1,0,3,2] row_mask:0xf bank_mask:0xf
	s_waitcnt lgkmcnt(0)
	v_max_u32_e32 v9, v9, v12
	s_nop 1
	v_mov_b32_dpp v12, v9 quad_perm:[2,3,0,1] row_mask:0xf bank_mask:0xf
	s_waitcnt lgkmcnt(0)
	v_max_u32_e32 v9, v9, v12
	s_nop 1
	v_mov_b32_dpp v12, v9 row_half_mirror row_mask:0xf bank_mask:0xf
	s_waitcnt lgkmcnt(0)
	v_max_u32_e32 v9, v9, v12
	v_cmp_lt_u32_e32 vcc, v11, v9
	s_nop 1
	v_cndmask_b32_e32 v12, 0, v11, vcc
	v_max_u32_e32 v13, v12, v6
	v_cmp_lt_u32_e32 vcc, v6, v9
	s_nop 1
	v_cndmask_b32_e32 v12, v12, v13, vcc
	v_max_u32_e32 v13, v12, v7
	v_cmp_lt_u32_e32 vcc, v7, v9
	s_nop 1
	v_cndmask_b32_e32 v12, v12, v13, vcc
	v_max_u32_e32 v13, v12, v10
	v_cmp_lt_u32_e32 vcc, v10, v9
	s_nop 1
	v_cndmask_b32_e32 v12, v12, v13, vcc
	v_max_u32_e32 v13, v12, v3
	v_cmp_lt_u32_e32 vcc, v3, v9
	s_nop 1
	v_cndmask_b32_e32 v12, v12, v13, vcc
	v_max_u32_e32 v13, v12, v2
	v_cmp_lt_u32_e32 vcc, v2, v9
	s_nop 1
	v_cndmask_b32_e32 v12, v12, v13, vcc
	v_max_u32_e32 v13, v12, v18
	v_cmp_lt_u32_e32 vcc, v18, v9
	s_nop 1
	v_cndmask_b32_e32 v12, v12, v13, vcc
	s_nop 1
	v_mov_b32_dpp v13, v12 quad_perm:[1,0,3,2] row_mask:0xf bank_mask:0xf
	s_waitcnt lgkmcnt(0)
	v_max_u32_e32 v12, v12, v13
	s_nop 1
	v_mov_b32_dpp v13, v12 quad_perm:[2,3,0,1] row_mask:0xf bank_mask:0xf
	s_waitcnt lgkmcnt(0)
	v_max_u32_e32 v12, v12, v13
	s_nop 1
	v_mov_b32_dpp v13, v12 row_half_mirror row_mask:0xf bank_mask:0xf
	s_waitcnt lgkmcnt(0)
	v_max_u32_e32 v17, v12, v13
	v_cmp_lt_u32_e32 vcc, v11, v17
	s_nop 1
	v_cndmask_b32_e32 v12, 0, v11, vcc
	v_max_u32_e32 v13, v12, v6
	v_cmp_lt_u32_e32 vcc, v6, v17
	s_nop 1
	v_cndmask_b32_e32 v12, v12, v13, vcc
	v_max_u32_e32 v13, v12, v7
	v_cmp_lt_u32_e32 vcc, v7, v17
	s_nop 1
	v_cndmask_b32_e32 v12, v12, v13, vcc
	v_max_u32_e32 v13, v12, v10
	v_cmp_lt_u32_e32 vcc, v10, v17
	s_nop 1
	v_cndmask_b32_e32 v12, v12, v13, vcc
	v_max_u32_e32 v13, v12, v3
	v_cmp_lt_u32_e32 vcc, v3, v17
	s_nop 1
	v_cndmask_b32_e32 v12, v12, v13, vcc
	v_max_u32_e32 v13, v12, v2
	v_cmp_lt_u32_e32 vcc, v2, v17
	s_nop 1
	v_cndmask_b32_e32 v12, v12, v13, vcc
	v_max_u32_e32 v13, v12, v18
	v_cmp_lt_u32_e32 vcc, v18, v17
	s_nop 1
	v_cndmask_b32_e32 v12, v12, v13, vcc
	s_nop 1
	v_mov_b32_dpp v13, v12 quad_perm:[1,0,3,2] row_mask:0xf bank_mask:0xf
	s_waitcnt lgkmcnt(0)
	v_max_u32_e32 v12, v12, v13
	s_nop 1
	v_mov_b32_dpp v13, v12 quad_perm:[2,3,0,1] row_mask:0xf bank_mask:0xf
	s_waitcnt lgkmcnt(0)
	v_max_u32_e32 v12, v12, v13
	s_nop 1
	v_mov_b32_dpp v13, v12 row_half_mirror row_mask:0xf bank_mask:0xf
	s_waitcnt lgkmcnt(0)
	v_max_u32_e32 v19, v12, v13
	v_cmp_lt_u32_e32 vcc, v11, v19
	s_nop 1
	v_cndmask_b32_e32 v12, 0, v11, vcc
	v_max_u32_e32 v13, v12, v6
	v_cmp_lt_u32_e32 vcc, v6, v19
	s_nop 1
	v_cndmask_b32_e32 v12, v12, v13, vcc
	v_max_u32_e32 v13, v12, v7
	v_cmp_lt_u32_e32 vcc, v7, v19
	s_nop 1
	v_cndmask_b32_e32 v12, v12, v13, vcc
	v_max_u32_e32 v13, v12, v10
	v_cmp_lt_u32_e32 vcc, v10, v19
	s_nop 1
	v_cndmask_b32_e32 v12, v12, v13, vcc
	v_max_u32_e32 v13, v12, v3
	v_cmp_lt_u32_e32 vcc, v3, v19
	s_nop 1
	v_cndmask_b32_e32 v12, v12, v13, vcc
	v_max_u32_e32 v13, v12, v2
	v_cmp_lt_u32_e32 vcc, v2, v19
	s_nop 1
	v_cndmask_b32_e32 v12, v12, v13, vcc
	v_max_u32_e32 v13, v12, v18
	v_cmp_lt_u32_e32 vcc, v18, v19
	s_nop 1
	v_cndmask_b32_e32 v12, v12, v13, vcc
	s_nop 1
	v_mov_b32_dpp v13, v12 quad_perm:[1,0,3,2] row_mask:0xf bank_mask:0xf
	s_waitcnt lgkmcnt(0)
	v_max_u32_e32 v12, v12, v13
	s_nop 1
	v_mov_b32_dpp v13, v12 quad_perm:[2,3,0,1] row_mask:0xf bank_mask:0xf
	s_waitcnt lgkmcnt(0)
	v_max_u32_e32 v12, v12, v13
	s_nop 1
	v_mov_b32_dpp v13, v12 row_half_mirror row_mask:0xf bank_mask:0xf
	s_waitcnt lgkmcnt(0)
	v_max_u32_e32 v34, v12, v13
	v_cmp_lt_u32_e32 vcc, v11, v34
	s_nop 1
	v_cndmask_b32_e32 v12, 0, v11, vcc
	v_max_u32_e32 v13, v12, v6
	v_cmp_lt_u32_e32 vcc, v6, v34
	s_nop 1
	v_cndmask_b32_e32 v12, v12, v13, vcc
	v_max_u32_e32 v13, v12, v7
	v_cmp_lt_u32_e32 vcc, v7, v34
	s_nop 1
	v_cndmask_b32_e32 v12, v12, v13, vcc
	v_max_u32_e32 v13, v12, v10
	v_cmp_lt_u32_e32 vcc, v10, v34
	s_nop 1
	v_cndmask_b32_e32 v12, v12, v13, vcc
	v_max_u32_e32 v13, v12, v3
	v_cmp_lt_u32_e32 vcc, v3, v34
	s_nop 1
	v_cndmask_b32_e32 v12, v12, v13, vcc
	v_max_u32_e32 v13, v12, v2
	v_cmp_lt_u32_e32 vcc, v2, v34
	s_nop 1
	v_cndmask_b32_e32 v12, v12, v13, vcc
	v_max_u32_e32 v13, v12, v18
	v_cmp_lt_u32_e32 vcc, v18, v34
	s_nop 1
	v_cndmask_b32_e32 v12, v12, v13, vcc
	s_nop 1
	v_mov_b32_dpp v13, v12 quad_perm:[1,0,3,2] row_mask:0xf bank_mask:0xf
	s_waitcnt lgkmcnt(0)
	v_max_u32_e32 v12, v12, v13
	s_nop 1
	v_mov_b32_dpp v13, v12 quad_perm:[2,3,0,1] row_mask:0xf bank_mask:0xf
	s_waitcnt lgkmcnt(0)
	v_max_u32_e32 v12, v12, v13
	s_nop 1
	v_mov_b32_dpp v13, v12 row_half_mirror row_mask:0xf bank_mask:0xf
	s_waitcnt lgkmcnt(0)
	v_max_u32_e32 v35, v12, v13
	v_cmp_lt_u32_e32 vcc, v11, v35
	s_nop 1
	v_cndmask_b32_e32 v12, 0, v11, vcc
	v_max_u32_e32 v13, v12, v6
	v_cmp_lt_u32_e32 vcc, v6, v35
	s_nop 1
	v_cndmask_b32_e32 v12, v12, v13, vcc
	v_max_u32_e32 v13, v12, v7
	v_cmp_lt_u32_e32 vcc, v7, v35
	s_nop 1
	v_cndmask_b32_e32 v12, v12, v13, vcc
	v_max_u32_e32 v13, v12, v10
	v_cmp_lt_u32_e32 vcc, v10, v35
	s_nop 1
	v_cndmask_b32_e32 v12, v12, v13, vcc
	v_max_u32_e32 v13, v12, v3
	v_cmp_lt_u32_e32 vcc, v3, v35
	s_nop 1
	v_cndmask_b32_e32 v12, v12, v13, vcc
	v_max_u32_e32 v13, v12, v2
	v_cmp_lt_u32_e32 vcc, v2, v35
	s_nop 1
	v_cndmask_b32_e32 v12, v12, v13, vcc
	v_max_u32_e32 v13, v12, v18
	v_cmp_lt_u32_e32 vcc, v18, v35
	s_nop 1
	v_cndmask_b32_e32 v12, v12, v13, vcc
	s_nop 1
	v_mov_b32_dpp v13, v12 quad_perm:[1,0,3,2] row_mask:0xf bank_mask:0xf
	s_waitcnt lgkmcnt(0)
	v_max_u32_e32 v12, v12, v13
	s_nop 1
	v_mov_b32_dpp v13, v12 quad_perm:[2,3,0,1] row_mask:0xf bank_mask:0xf
	s_waitcnt lgkmcnt(0)
	v_max_u32_e32 v12, v12, v13
	s_nop 1
	v_mov_b32_dpp v13, v12 row_half_mirror row_mask:0xf bank_mask:0xf
	s_waitcnt lgkmcnt(0)
	v_max_u32_e32 v36, v12, v13
	v_cmp_lt_u32_e32 vcc, v11, v36
	s_nop 1
	v_cndmask_b32_e32 v12, 0, v11, vcc
	v_max_u32_e32 v13, v12, v6
	v_cmp_lt_u32_e32 vcc, v6, v36
	s_nop 1
	v_cndmask_b32_e32 v12, v12, v13, vcc
	v_max_u32_e32 v13, v12, v7
	v_cmp_lt_u32_e32 vcc, v7, v36
	s_nop 1
	v_cndmask_b32_e32 v12, v12, v13, vcc
	v_max_u32_e32 v13, v12, v10
	v_cmp_lt_u32_e32 vcc, v10, v36
	s_nop 1
	v_cndmask_b32_e32 v12, v12, v13, vcc
	v_max_u32_e32 v13, v12, v3
	v_cmp_lt_u32_e32 vcc, v3, v36
	s_nop 1
	v_cndmask_b32_e32 v12, v12, v13, vcc
	v_max_u32_e32 v13, v12, v2
	v_cmp_lt_u32_e32 vcc, v2, v36
	s_nop 1
	v_cndmask_b32_e32 v12, v12, v13, vcc
	v_max_u32_e32 v13, v12, v18
	v_cmp_lt_u32_e32 vcc, v18, v36
	s_nop 1
	v_cndmask_b32_e32 v12, v12, v13, vcc
	s_nop 1
	v_mov_b32_dpp v13, v12 quad_perm:[1,0,3,2] row_mask:0xf bank_mask:0xf
	s_waitcnt lgkmcnt(0)
	v_max_u32_e32 v12, v12, v13
	s_nop 1
	v_mov_b32_dpp v13, v12 quad_perm:[2,3,0,1] row_mask:0xf bank_mask:0xf
	s_waitcnt lgkmcnt(0)
	v_max_u32_e32 v12, v12, v13
	s_nop 1
	v_mov_b32_dpp v13, v12 row_half_mirror row_mask:0xf bank_mask:0xf
	s_waitcnt lgkmcnt(0)
	v_max_u32_e32 v37, v12, v13
	v_cmp_lt_u32_e32 vcc, v11, v37
	s_nop 1
	v_cndmask_b32_e32 v12, 0, v11, vcc
	v_max_u32_e32 v13, v12, v6
	v_cmp_lt_u32_e32 vcc, v6, v37
	s_nop 1
	v_cndmask_b32_e32 v12, v12, v13, vcc
	v_max_u32_e32 v13, v12, v7
	v_cmp_lt_u32_e32 vcc, v7, v37
	s_nop 1
	v_cndmask_b32_e32 v12, v12, v13, vcc
	v_max_u32_e32 v13, v12, v10
	v_cmp_lt_u32_e32 vcc, v10, v37
	s_nop 1
	v_cndmask_b32_e32 v12, v12, v13, vcc
	v_max_u32_e32 v13, v12, v3
	v_cmp_lt_u32_e32 vcc, v3, v37
	s_nop 1
	v_cndmask_b32_e32 v12, v12, v13, vcc
	v_max_u32_e32 v13, v12, v2
	v_cmp_lt_u32_e32 vcc, v2, v37
	s_nop 1
	v_cndmask_b32_e32 v12, v12, v13, vcc
	v_max_u32_e32 v13, v12, v18
	v_cmp_lt_u32_e32 vcc, v18, v37
	s_nop 1
	v_cndmask_b32_e32 v12, v12, v13, vcc
	s_nop 1
	v_mov_b32_dpp v13, v12 quad_perm:[1,0,3,2] row_mask:0xf bank_mask:0xf
	s_waitcnt lgkmcnt(0)
	v_max_u32_e32 v12, v12, v13
	s_nop 1
	v_mov_b32_dpp v13, v12 quad_perm:[2,3,0,1] row_mask:0xf bank_mask:0xf
	s_waitcnt lgkmcnt(0)
	v_max_u32_e32 v12, v12, v13
	s_nop 1
	v_mov_b32_dpp v13, v12 row_half_mirror row_mask:0xf bank_mask:0xf
	s_waitcnt lgkmcnt(0)
	v_max_u32_e32 v38, v12, v13
	v_cmp_lt_u32_e32 vcc, v11, v38
	s_nop 1
	v_cndmask_b32_e32 v12, 0, v11, vcc
	v_max_u32_e32 v13, v12, v6
	v_cmp_lt_u32_e32 vcc, v6, v38
	s_nop 1
	v_cndmask_b32_e32 v12, v12, v13, vcc
	v_max_u32_e32 v13, v12, v7
	v_cmp_lt_u32_e32 vcc, v7, v38
	s_nop 1
	v_cndmask_b32_e32 v12, v12, v13, vcc
	v_max_u32_e32 v13, v12, v10
	v_cmp_lt_u32_e32 vcc, v10, v38
	s_nop 1
	v_cndmask_b32_e32 v12, v12, v13, vcc
	v_max_u32_e32 v13, v12, v3
	v_cmp_lt_u32_e32 vcc, v3, v38
	s_nop 1
	v_cndmask_b32_e32 v12, v12, v13, vcc
	v_max_u32_e32 v13, v12, v2
	v_cmp_lt_u32_e32 vcc, v2, v38
	s_nop 1
	v_cndmask_b32_e32 v12, v12, v13, vcc
	v_max_u32_e32 v13, v12, v18
	v_cmp_lt_u32_e32 vcc, v18, v38
	s_nop 1
	v_cndmask_b32_e32 v12, v12, v13, vcc
	s_nop 1
	v_mov_b32_dpp v13, v12 quad_perm:[1,0,3,2] row_mask:0xf bank_mask:0xf
	s_waitcnt lgkmcnt(0)
	v_max_u32_e32 v12, v12, v13
	s_nop 1
	v_mov_b32_dpp v13, v12 quad_perm:[2,3,0,1] row_mask:0xf bank_mask:0xf
	s_waitcnt lgkmcnt(0)
	v_max_u32_e32 v12, v12, v13
	s_nop 1
	v_mov_b32_dpp v13, v12 row_half_mirror row_mask:0xf bank_mask:0xf
	s_waitcnt lgkmcnt(0)
	v_max_u32_e32 v39, v12, v13
	v_cmp_lt_u32_e32 vcc, v11, v39
	s_nop 1
	v_cndmask_b32_e32 v12, 0, v11, vcc
	v_max_u32_e32 v13, v12, v6
	v_cmp_lt_u32_e32 vcc, v6, v39
	s_nop 1
	v_cndmask_b32_e32 v12, v12, v13, vcc
	v_max_u32_e32 v13, v12, v7
	v_cmp_lt_u32_e32 vcc, v7, v39
	s_nop 1
	v_cndmask_b32_e32 v12, v12, v13, vcc
	v_max_u32_e32 v13, v12, v10
	v_cmp_lt_u32_e32 vcc, v10, v39
	s_nop 1
	v_cndmask_b32_e32 v12, v12, v13, vcc
	v_max_u32_e32 v13, v12, v3
	v_cmp_lt_u32_e32 vcc, v3, v39
	s_nop 1
	v_cndmask_b32_e32 v12, v12, v13, vcc
	v_max_u32_e32 v13, v12, v2
	v_cmp_lt_u32_e32 vcc, v2, v39
	s_nop 1
	v_cndmask_b32_e32 v12, v12, v13, vcc
	v_max_u32_e32 v13, v12, v18
	v_cmp_lt_u32_e32 vcc, v18, v39
	s_nop 1
	v_cndmask_b32_e32 v12, v12, v13, vcc
	s_nop 1
	v_mov_b32_dpp v13, v12 quad_perm:[1,0,3,2] row_mask:0xf bank_mask:0xf
	s_waitcnt lgkmcnt(0)
	v_max_u32_e32 v12, v12, v13
	s_nop 1
	v_mov_b32_dpp v13, v12 quad_perm:[2,3,0,1] row_mask:0xf bank_mask:0xf
	s_waitcnt lgkmcnt(0)
	v_max_u32_e32 v12, v12, v13
	s_nop 1
	v_mov_b32_dpp v13, v12 row_half_mirror row_mask:0xf bank_mask:0xf
	s_waitcnt lgkmcnt(0)
	v_max_u32_e32 v40, v12, v13
	v_cmp_lt_u32_e32 vcc, v11, v40
	s_nop 1
	v_cndmask_b32_e32 v12, 0, v11, vcc
	v_max_u32_e32 v13, v12, v6
	v_cmp_lt_u32_e32 vcc, v6, v40
	s_nop 1
	v_cndmask_b32_e32 v12, v12, v13, vcc
	v_max_u32_e32 v13, v12, v7
	v_cmp_lt_u32_e32 vcc, v7, v40
	s_nop 1
	v_cndmask_b32_e32 v12, v12, v13, vcc
	v_max_u32_e32 v13, v12, v10
	v_cmp_lt_u32_e32 vcc, v10, v40
	s_nop 1
	v_cndmask_b32_e32 v12, v12, v13, vcc
	v_max_u32_e32 v13, v12, v3
	v_cmp_lt_u32_e32 vcc, v3, v40
	s_nop 1
	v_cndmask_b32_e32 v12, v12, v13, vcc
	v_max_u32_e32 v13, v12, v2
	v_cmp_lt_u32_e32 vcc, v2, v40
	s_nop 1
	v_cndmask_b32_e32 v12, v12, v13, vcc
	v_max_u32_e32 v13, v12, v18
	v_cmp_lt_u32_e32 vcc, v18, v40
	s_nop 1
	v_cndmask_b32_e32 v12, v12, v13, vcc
	s_nop 1
	v_mov_b32_dpp v13, v12 quad_perm:[1,0,3,2] row_mask:0xf bank_mask:0xf
	s_waitcnt lgkmcnt(0)
	v_max_u32_e32 v14, v12, v13
	s_nop 1
	v_mov_b32_dpp v15, v14 quad_perm:[2,3,0,1] row_mask:0xf bank_mask:0xf
	v_lshlrev_b64 v[12:13], 8, v[0:1]
	v_lshlrev_b64 v[0:1], 12, v[0:1]
	v_lshl_add_u64 v[0:1], v[114:115], 0, v[0:1]
	v_lshl_add_u64 v[32:33], s[30:31], 0, v[12:13]
	s_waitcnt lgkmcnt(0)
	v_max_u32_e32 v24, v14, v15
	s_nop 1
	v_mov_b32_dpp v25, v24 row_half_mirror row_mask:0xf bank_mask:0xf
	global_load_dwordx4 v[12:15], v[0:1], off
	global_load_dwordx4 v[20:23], v[0:1], off offset:1024
	s_waitcnt lgkmcnt(0)
	v_max_u32_e32 v41, v24, v25
	v_cmp_lt_u32_e32 vcc, v11, v41
	s_nop 1
	v_cndmask_b32_e32 v24, 0, v11, vcc
	v_max_u32_e32 v25, v24, v6
	v_cmp_lt_u32_e32 vcc, v6, v41
	s_nop 1
	v_cndmask_b32_e32 v24, v24, v25, vcc
	v_max_u32_e32 v25, v24, v7
	v_cmp_lt_u32_e32 vcc, v7, v41
	s_nop 1
	v_cndmask_b32_e32 v24, v24, v25, vcc
	v_max_u32_e32 v25, v24, v10
	v_cmp_lt_u32_e32 vcc, v10, v41
	s_nop 1
	v_cndmask_b32_e32 v24, v24, v25, vcc
	v_max_u32_e32 v25, v24, v3
	v_cmp_lt_u32_e32 vcc, v3, v41
	s_nop 1
	v_cndmask_b32_e32 v24, v24, v25, vcc
	v_max_u32_e32 v25, v24, v2
	v_cmp_lt_u32_e32 vcc, v2, v41
	s_nop 1
	v_cndmask_b32_e32 v24, v24, v25, vcc
	v_max_u32_e32 v25, v24, v18
	v_cmp_lt_u32_e32 vcc, v18, v41
	s_nop 1
	v_cndmask_b32_e32 v42, v24, v25, vcc
	s_nop 1
	v_mov_b32_dpp v43, v42 quad_perm:[1,0,3,2] row_mask:0xf bank_mask:0xf
	global_load_dwordx4 v[24:27], v[0:1], off offset:2048
	global_load_dwordx4 v[28:31], v[0:1], off offset:3072
	v_cndmask_b32_e64 v0, 0, v4, s[26:27]
	v_cndmask_b32_e64 v1, 0, v5, s[26:27]
	v_cndmask_b32_e64 v0, v0, v8, s[2:3]
	s_waitcnt lgkmcnt(0)
	v_max_u32_e32 v4, v42, v43
	s_nop 1
	v_mov_b32_dpp v5, v4 quad_perm:[2,3,0,1] row_mask:0xf bank_mask:0xf
	v_cndmask_b32_e64 v1, v1, v9, s[2:3]
	v_cndmask_b32_e64 v1, v1, v19, s[4:5]
	v_cndmask_b32_e64 v1, v1, v35, s[6:7]
	v_cndmask_b32_e64 v1, v1, v37, s[8:9]
	s_waitcnt lgkmcnt(0)
	v_max_u32_e32 v4, v4, v5
	s_nop 1
	v_mov_b32_dpp v5, v4 row_half_mirror row_mask:0xf bank_mask:0xf
	v_cndmask_b32_e64 v1, v1, v39, s[10:11]
	v_cndmask_b32_e64 v0, v0, v17, s[4:5]
	v_cndmask_b32_e64 v0, v0, v34, s[6:7]
	v_cndmask_b32_e64 v0, v0, v36, s[8:9]
	s_waitcnt lgkmcnt(0)
	v_max_u32_e32 v4, v4, v5
	v_cmp_lt_u32_e32 vcc, v11, v4
	v_cndmask_b32_e64 v0, v0, v38, s[10:11]
	v_cndmask_b32_e64 v0, v0, v40, s[12:13]
	v_cndmask_b32_e32 v5, 0, v11, vcc
	v_max_u32_e32 v8, v5, v6
	v_cmp_lt_u32_e32 vcc, v6, v4
	v_cndmask_b32_e64 v17, v0, v4, s[14:15]
	v_not_b32_e32 v0, v17
	v_cndmask_b32_e32 v5, v5, v8, vcc
	v_max_u32_e32 v6, v5, v7
	v_cmp_lt_u32_e32 vcc, v7, v4
	v_lshrrev_b32_e32 v0, 4, v0
	v_and_or_b32 v106, v0, 15, v104
	v_cndmask_b32_e32 v5, v5, v6, vcc
	v_max_u32_e32 v6, v5, v10
	v_cmp_lt_u32_e32 vcc, v10, v4
	s_nop 1
	v_cndmask_b32_e32 v5, v5, v6, vcc
	v_max_u32_e32 v6, v5, v3
	v_cmp_lt_u32_e32 vcc, v3, v4
	s_nop 1
	v_cndmask_b32_e32 v3, v5, v6, vcc
	v_max_u32_e32 v5, v3, v2
	v_cmp_lt_u32_e32 vcc, v2, v4
	s_nop 1
	v_cndmask_b32_e32 v2, v3, v5, vcc
	v_max_u32_e32 v3, v2, v18
	v_cmp_lt_u32_e32 vcc, v18, v4
	v_cndmask_b32_e64 v5, v1, v41, s[12:13]
	s_nop 0
	v_cndmask_b32_e32 v2, v2, v3, vcc
	s_nop 1
	v_mov_b32_dpp v3, v2 quad_perm:[1,0,3,2] row_mask:0xf bank_mask:0xf
	v_cmp_gt_i32_e32 vcc, 0, v17
	s_waitcnt lgkmcnt(0)
	v_max_u32_e32 v1, v2, v3
	s_nop 1
	v_mov_b32_dpp v2, v1 quad_perm:[2,3,0,1] row_mask:0xf bank_mask:0xf
	v_bitop3_b32 v3, v17, 15, v17 bitop3:0xc
	s_waitcnt lgkmcnt(0)
	v_max_u32_e32 v4, v1, v2
	s_nop 1
	v_mov_b32_dpp v6, v4 row_half_mirror row_mask:0xf bank_mask:0xf
	v_lshl_add_u64 v[0:1], v[32:33], 0, v[106:107]
	v_add_u32_e32 v106, v3, v104
	v_lshl_add_u64 v[2:3], v[32:33], 0, v[106:107]
	s_waitcnt lgkmcnt(0)
	v_max_u32_e32 v4, v4, v6
	v_cndmask_b32_e64 v34, v5, v4, s[14:15]
	v_not_b32_e32 v4, v34
	v_lshrrev_b32_e32 v4, 4, v4
	v_bitop3_b32 v6, v34, 15, v34 bitop3:0xc
	v_and_or_b32 v106, v4, 15, v104
	v_lshl_add_u64 v[4:5], v[32:33], 0, v[106:107]
	v_add_u32_e32 v106, v6, v104
	v_lshl_add_u64 v[6:7], v[32:33], 0, v[106:107]
	global_load_ubyte v18, v[0:1], off
	global_load_ubyte v19, v[2:3], off offset:16
	global_load_ubyte v32, v[4:5], off
	global_load_ubyte v33, v[6:7], off offset:16
	s_waitcnt vmcnt(7)
	ds_write_b128 v163, v[12:15]
	s_waitcnt vmcnt(6)
	ds_write_b128 v163, v[20:23] offset:1280
	s_waitcnt vmcnt(5)
	ds_write_b128 v163, v[24:27] offset:2560
	s_waitcnt vmcnt(4)
	ds_write_b128 v163, v[28:31] offset:3840
	s_waitcnt lgkmcnt(0)
	ds_read_b128 v[0:3], v164
	ds_read_b128 v[4:7], v164 offset:16
	ds_read_b128 v[8:11], v164 offset:32
	ds_read_b128 v[12:15], v164 offset:48
	s_waitcnt lgkmcnt(0)
	v_and_b32_e32 v22, 0x7fffff00, v17
	v_bitop3_b32 v23, v17, s50, v17 bitop3:0xcf
	v_cndmask_b32_e32 v17, v23, v22, vcc
	v_and_b32_e32 v23, 0x7fffff00, v34
	v_bitop3_b32 v24, v34, s50, v34 bitop3:0xcf
	v_cmp_gt_i32_e32 vcc, 0, v34
	v_max_f32_e32 v22, v17, v17
	v_xor_b32_e32 v25, 32, v168
	v_cndmask_b32_e32 v23, v24, v23, vcc
	v_max_f32_e32 v24, v23, v23
	v_max_f32_e32 v22, v22, v24
	s_nop 1
	v_mov_b32_dpp v24, v22 quad_perm:[1,0,3,2] row_mask:0xf bank_mask:0xf
	v_xor_b32_e32 v26, 16, v168
	v_cmp_lt_i32_e32 vcc, v25, v16
	v_xor_b32_e32 v27, 8, v168
	v_add3_u32 v28, v157, s44, v112
	s_waitcnt lgkmcnt(0)
	v_max_f32_e32 v24, v24, v24
	v_max_f32_e32 v22, v22, v24
	s_nop 1
	v_mov_b32_dpp v24, v22 quad_perm:[2,3,0,1] row_mask:0xf bank_mask:0xf
	v_cndmask_b32_e32 v25, v168, v25, vcc
	v_cmp_lt_i32_e32 vcc, v26, v16
	v_lshlrev_b32_e32 v70, 2, v25
	s_waitcnt lgkmcnt(0)
	v_max_f32_e32 v24, v24, v24
	v_max_f32_e32 v22, v22, v24
	s_nop 1
	v_mov_b32_dpp v24, v22 row_half_mirror row_mask:0xf bank_mask:0xf
	v_cndmask_b32_e32 v26, v168, v26, vcc
	v_cmp_lt_i32_e32 vcc, v27, v16
	v_lshlrev_b32_e32 v71, 2, v26
	s_waitcnt lgkmcnt(0)
	v_max_f32_e32 v24, v24, v24
	v_max_f32_e32 v22, v22, v24
	v_sub_f32_e32 v17, v17, v22
	v_sub_f32_e32 v22, v23, v22
	v_mul_f32_e32 v17, 0x3fb8aa3b, v17
	v_mul_f32_e32 v23, 0x3fb8aa3b, v22
	v_exp_f32_e32 v22, v17
	v_exp_f32_e32 v23, v23
	v_cndmask_b32_e32 v27, v168, v27, vcc
	v_lshlrev_b32_e32 v72, 2, v27
	v_add_f32_e32 v17, v22, v23
	s_nop 1
	v_mov_b32_dpp v24, v17 quad_perm:[1,0,3,2] row_mask:0xf bank_mask:0xf
	s_waitcnt lgkmcnt(0)
	v_add_f32_e32 v17, v17, v24
	s_nop 1
	v_mov_b32_dpp v24, v17 quad_perm:[2,3,0,1] row_mask:0xf bank_mask:0xf
	s_waitcnt lgkmcnt(0)
	v_add_f32_e32 v17, v17, v24
	s_nop 1
	v_mov_b32_dpp v24, v17 row_half_mirror row_mask:0xf bank_mask:0xf
	s_waitcnt lgkmcnt(0)
	v_add_f32_e32 v16, v17, v24
	v_div_scale_f32 v17, s[44:45], v16, v16, 1.0
	v_rcp_f32_e32 v24, v17
	v_div_scale_f32 v25, vcc, 1.0, v16, 1.0
	v_fma_f32 v26, -v17, v24, 1.0
	v_fmac_f32_e32 v24, v26, v24
	v_mul_f32_e32 v26, v25, v24
	v_fma_f32 v29, -v17, v26, v25
	v_fmac_f32_e32 v26, v29, v24
	s_waitcnt vmcnt(2)
	v_lshl_add_u32 v64, v18, 7, v19
	v_lshlrev_b32_e32 v20, 2, v64
	s_waitcnt vmcnt(0)
	v_lshl_add_u32 v65, v32, 7, v33
	v_lshlrev_b32_e32 v21, 2, v65
	global_load_dword v18, v20, s[36:37]
	global_load_dword v19, v21, s[36:37]
	s_nop 0
	global_load_dword v21, v21, s[34:35]
	s_nop 0
	global_load_dword v20, v20, s[34:35]
	v_fma_f32 v17, -v17, v26, v25
	v_div_fmas_f32 v17, v17, v24, v26
	v_div_fixup_f32 v16, v17, v16, 1.0
	v_pk_mul_f32 v[16:17], v[22:23], v[16:17] op_sel_hi:[1,0]
	s_waitcnt vmcnt(2)
	v_pk_mul_f32 v[16:17], v[18:19], v[16:17]
	v_lshrrev_b32_e32 v40, 11, v64
	v_lshrrev_b32_e32 v41, 11, v65
	v_mov_b32_e32 v44, 0
	v_mov_b32_e32 v45, 0
	s_mov_b32 s70, 0
	v_cmp_eq_u32_e64 s[66:67], 0, v40
	v_cmp_eq_u32_e64 s[68:69], 0, v41
	s_bcnt1_i32_b64 s71, s[66:67]
	s_bcnt1_i32_b64 s72, s[68:69]
	v_mbcnt_lo_u32_b32 v42, s66, 0
	v_mbcnt_hi_u32_b32 v42, s67, v42
	v_mbcnt_lo_u32_b32 v43, s68, 0
	v_mbcnt_hi_u32_b32 v43, s69, v43
	v_add_u32_e32 v42, s70, v42
	s_add_i32 s70, s70, s71
	v_add_u32_e32 v43, s70, v43
	s_add_i32 s70, s70, s72
	v_cndmask_b32_e64 v44, v44, v42, s[66:67]
	v_cndmask_b32_e64 v45, v45, v43, s[68:69]
	v_cmp_eq_u32_e64 s[66:67], 1, v40
	v_cmp_eq_u32_e64 s[68:69], 1, v41
	s_bcnt1_i32_b64 s71, s[66:67]
	s_bcnt1_i32_b64 s72, s[68:69]
	v_mbcnt_lo_u32_b32 v42, s66, 0
	v_mbcnt_hi_u32_b32 v42, s67, v42
	v_mbcnt_lo_u32_b32 v43, s68, 0
	v_mbcnt_hi_u32_b32 v43, s69, v43
	v_add_u32_e32 v42, s70, v42
	s_add_i32 s70, s70, s71
	v_add_u32_e32 v43, s70, v43
	s_add_i32 s70, s70, s72
	v_cndmask_b32_e64 v44, v44, v42, s[66:67]
	v_cndmask_b32_e64 v45, v45, v43, s[68:69]
	v_cmp_eq_u32_e64 s[66:67], 2, v40
	v_cmp_eq_u32_e64 s[68:69], 2, v41
	s_bcnt1_i32_b64 s71, s[66:67]
	s_bcnt1_i32_b64 s72, s[68:69]
	v_mbcnt_lo_u32_b32 v42, s66, 0
	v_mbcnt_hi_u32_b32 v42, s67, v42
	v_mbcnt_lo_u32_b32 v43, s68, 0
	v_mbcnt_hi_u32_b32 v43, s69, v43
	v_add_u32_e32 v42, s70, v42
	s_add_i32 s70, s70, s71
	v_add_u32_e32 v43, s70, v43
	s_add_i32 s70, s70, s72
	v_cndmask_b32_e64 v44, v44, v42, s[66:67]
	v_cndmask_b32_e64 v45, v45, v43, s[68:69]
	v_cmp_eq_u32_e64 s[66:67], 3, v40
	v_cmp_eq_u32_e64 s[68:69], 3, v41
	s_bcnt1_i32_b64 s71, s[66:67]
	s_bcnt1_i32_b64 s72, s[68:69]
	v_mbcnt_lo_u32_b32 v42, s66, 0
	v_mbcnt_hi_u32_b32 v42, s67, v42
	v_mbcnt_lo_u32_b32 v43, s68, 0
	v_mbcnt_hi_u32_b32 v43, s69, v43
	v_add_u32_e32 v42, s70, v42
	s_add_i32 s70, s70, s71
	v_add_u32_e32 v43, s70, v43
	s_add_i32 s70, s70, s72
	v_cndmask_b32_e64 v44, v44, v42, s[66:67]
	v_cndmask_b32_e64 v45, v45, v43, s[68:69]
	v_cmp_eq_u32_e64 s[66:67], 4, v40
	v_cmp_eq_u32_e64 s[68:69], 4, v41
	s_bcnt1_i32_b64 s71, s[66:67]
	s_bcnt1_i32_b64 s72, s[68:69]
	v_mbcnt_lo_u32_b32 v42, s66, 0
	v_mbcnt_hi_u32_b32 v42, s67, v42
	v_mbcnt_lo_u32_b32 v43, s68, 0
	v_mbcnt_hi_u32_b32 v43, s69, v43
	v_add_u32_e32 v42, s70, v42
	s_add_i32 s70, s70, s71
	v_add_u32_e32 v43, s70, v43
	s_add_i32 s70, s70, s72
	v_cndmask_b32_e64 v44, v44, v42, s[66:67]
	v_cndmask_b32_e64 v45, v45, v43, s[68:69]
	v_cmp_eq_u32_e64 s[66:67], 5, v40
	v_cmp_eq_u32_e64 s[68:69], 5, v41
	s_bcnt1_i32_b64 s71, s[66:67]
	s_bcnt1_i32_b64 s72, s[68:69]
	v_mbcnt_lo_u32_b32 v42, s66, 0
	v_mbcnt_hi_u32_b32 v42, s67, v42
	v_mbcnt_lo_u32_b32 v43, s68, 0
	v_mbcnt_hi_u32_b32 v43, s69, v43
	v_add_u32_e32 v42, s70, v42
	s_add_i32 s70, s70, s71
	v_add_u32_e32 v43, s70, v43
	s_add_i32 s70, s70, s72
	v_cndmask_b32_e64 v44, v44, v42, s[66:67]
	v_cndmask_b32_e64 v45, v45, v43, s[68:69]
	v_cmp_eq_u32_e64 s[66:67], 6, v40
	v_cmp_eq_u32_e64 s[68:69], 6, v41
	s_bcnt1_i32_b64 s71, s[66:67]
	s_bcnt1_i32_b64 s72, s[68:69]
	v_mbcnt_lo_u32_b32 v42, s66, 0
	v_mbcnt_hi_u32_b32 v42, s67, v42
	v_mbcnt_lo_u32_b32 v43, s68, 0
	v_mbcnt_hi_u32_b32 v43, s69, v43
	v_add_u32_e32 v42, s70, v42
	s_add_i32 s70, s70, s71
	v_add_u32_e32 v43, s70, v43
	s_add_i32 s70, s70, s72
	v_cndmask_b32_e64 v44, v44, v42, s[66:67]
	v_cndmask_b32_e64 v45, v45, v43, s[68:69]
	v_cmp_eq_u32_e64 s[66:67], 7, v40
	v_cmp_eq_u32_e64 s[68:69], 7, v41
	s_bcnt1_i32_b64 s71, s[66:67]
	s_bcnt1_i32_b64 s72, s[68:69]
	v_mbcnt_lo_u32_b32 v42, s66, 0
	v_mbcnt_hi_u32_b32 v42, s67, v42
	v_mbcnt_lo_u32_b32 v43, s68, 0
	v_mbcnt_hi_u32_b32 v43, s69, v43
	v_add_u32_e32 v42, s70, v42
	s_add_i32 s70, s70, s71
	v_add_u32_e32 v43, s70, v43
	s_add_i32 s70, s70, s72
	v_cndmask_b32_e64 v44, v44, v42, s[66:67]
	v_cndmask_b32_e64 v45, v45, v43, s[68:69]
	v_lshlrev_b32_e32 v46, 3, v168
	v_sub_u32_e32 v47, v159, v46
	v_sub_u32_e32 v46, v28, v46
	v_lshl_add_u32 v48, v44, 2, v46
	v_lshl_add_u32 v49, v45, 2, v46
	v_lshl_add_u32 v50, v44, 2, v47
	v_lshl_add_u32 v51, v45, 2, v47
	s_waitcnt vmcnt(0)
	ds_write_b32 v48, v64 offset:8704
	ds_write_b32 v49, v65 offset:8704
	ds_write_b32 v50, v16
	ds_write_b32 v51, v17
	ds_write_b32 v50, v20 offset:512
	ds_write_b32 v51, v21 offset:512
	ds_read_b64 v[64:65], v28 offset:8704
	s_waitcnt lgkmcnt(0)
	s_add_i32 s65, s47, -7
	v_readlane_b32 s44, v64, s65
	s_lshl_b32 s44, s44, 10
	s_add_u32 s66, s92, s44
	s_addc_u32 s67, s93, 0
	global_load_dwordx4 v[44:47], v200, s[66:67]
	v_readlane_b32 s44, v65, s65
	s_lshl_b32 s44, s44, 10
	s_add_u32 s66, s92, s44
	s_addc_u32 s67, s93, 0
	global_load_dwordx4 v[48:51], v201, s[66:67]
	s_add_i32 s65, s47, -6
	v_readlane_b32 s44, v64, s65
	s_lshl_b32 s44, s44, 10
	s_add_u32 s66, s92, s44
	s_addc_u32 s67, s93, 0
	global_load_dwordx4 v[52:55], v202, s[66:67]
	v_readlane_b32 s44, v65, s65
	s_lshl_b32 s44, s44, 10
	s_add_u32 s66, s92, s44
	s_addc_u32 s67, s93, 0
	global_load_dwordx4 v[56:59], v203, s[66:67]
	s_add_i32 s65, s47, -5
	v_readlane_b32 s44, v64, s65
	s_lshl_b32 s44, s44, 10
	s_add_u32 s66, s92, s44
	s_addc_u32 s67, s93, 0
	global_load_dwordx4 v[60:63], v204, s[66:67]
	v_readlane_b32 s44, v65, s65
	s_lshl_b32 s44, s44, 10
	s_add_u32 s66, s92, s44
	s_addc_u32 s67, s93, 0
	global_load_dwordx4 v[76:79], v205, s[66:67]
	s_add_i32 s65, s47, -4
	v_readlane_b32 s44, v64, s65
	s_lshl_b32 s44, s44, 10
	s_add_u32 s66, s92, s44
	s_addc_u32 s67, s93, 0
	global_load_dwordx4 v[80:83], v206, s[66:67]
	v_readlane_b32 s44, v65, s65
	s_lshl_b32 s44, s44, 10
	s_add_u32 s66, s92, s44
	s_addc_u32 s67, s93, 0
	global_load_dwordx4 v[84:87], v207, s[66:67]
	s_add_i32 s65, s47, -3
	v_readlane_b32 s44, v64, s65
	s_lshl_b32 s44, s44, 10
	s_add_u32 s66, s92, s44
	s_addc_u32 s67, s93, 0
	global_load_dwordx4 v[88:91], v208, s[66:67]
	v_readlane_b32 s44, v65, s65
	s_lshl_b32 s44, s44, 10
	s_add_u32 s66, s92, s44
	s_addc_u32 s67, s93, 0
	global_load_dwordx4 v[92:95], v209, s[66:67]
	s_add_i32 s65, s47, -2
	v_readlane_b32 s44, v64, s65
	s_lshl_b32 s44, s44, 10
	s_add_u32 s66, s92, s44
	s_addc_u32 s67, s93, 0
	global_load_dwordx4 v[96:99], v210, s[66:67]
	v_readlane_b32 s44, v65, s65
	s_lshl_b32 s44, s44, 10
	s_add_u32 s66, s92, s44
	s_addc_u32 s67, s93, 0
	global_load_dwordx4 v[100:103], v211, s[66:67]
	s_add_i32 s65, s47, -1
	v_readlane_b32 s44, v64, s65
	s_lshl_b32 s44, s44, 10
	s_add_u32 s66, s92, s44
	s_addc_u32 s67, s93, 0
	global_load_dwordx4 v[172:175], v212, s[66:67]
	v_readlane_b32 s44, v65, s65
	s_lshl_b32 s44, s44, 10
	s_add_u32 s66, s92, s44
	s_addc_u32 s67, s93, 0
	global_load_dwordx4 v[176:179], v213, s[66:67]
	s_add_i32 s65, s47, 0
	v_readlane_b32 s44, v64, s65
	s_lshl_b32 s44, s44, 10
	s_add_u32 s66, s92, s44
	s_addc_u32 s67, s93, 0
	global_load_dwordx4 v[180:183], v214, s[66:67]
	v_readlane_b32 s44, v65, s65
	s_lshl_b32 s44, s44, 10
	s_add_u32 s66, s92, s44
	s_addc_u32 s67, s93, 0
	global_load_dwordx4 v[184:187], v215, s[66:67]
